# w_ffn_up conversion entirely in the P7 slack on workgroups 64..255; P1 converts 3072 fewer items
# baseline (speedup 1.0000x reference)
; #define LAS __attribute__((address_space(3)))
; template <int PART> __device__ __forceinline__ void phase0(const Params& p, LAS unsigned char* lds) {
;     constexpr int SKIP = PART == 0 ? 0 : PART == 1 ? 48 : 192;
;     const int tid = threadIdx.x, lane = tid & 63, wave = tid >> 6;
;     const int gw = ((int)blockIdx.x - SKIP) * NWAVES + wave, NGW = ((int)gridDim.x - SKIP) * NWAVES;
;     if (gw < 0) return;
;     const int gt = blockIdx.x * NTHREADS + tid, NGT = gridDim.x * NTHREADS;
;     unsigned char* ws = p.ws;
;     LAS float* scr = (LAS float*)(lds + wave * 16640);
;     constexpr int I0 = 32 * 192, I1 = 32 * 112, I2 = 32 * 192, I3 = 96 * 32, I4 = 32 * 32, I5 = 32 * 32, I6 = 16 * 32, I7 = 64, I8 = 128, I9 = 128;
;     constexpr int NIT = I0 + I1 + I2 + I3 + I4 + I5 + I6 + I7 + I8 + I9;
;     constexpr int U0 = I0 + I1, U1 = U0 + I2 / 2, D0 = I0 + I1 + I2, D1 = D0 + I3;
;     constexpr int CUT = (U1 - U0) + I3;
;     constexpr int LO = PART == 0 ? 0 : PART == 1 ? I0 : PART == 2 ? U0 : D0, HI = PART == 0 ? I0 : PART == 1 ? NIT - CUT : PART == 2 ? U1 : D1;
;     for (int it0 = LO + gw; it0 < HI; it0 += NGW) {
;         int it = it0;
;         if (PART == 1) { if (it >= U0) it += U1 - U0; if (it >= D0) it += I3; }
;         int r = it;
;         if (r < I0) { const int nb = r % 192, kb = r / 192; cvt_item(p.in[I_WADA], NADA, (bf16_t*)(ws + WS_WADA), DM, 64 * kb, 64 * nb, 64 * nb, scr, lane); continue; } r -= I0;
;         if (r < I1) { const int nb = r % 112, kb = r / 112; cvt_item(p.in[I_WIN], INW, (bf16_t*)(ws + WS_WIN), DM, 64 * kb, 64 * nb, 64 * nb, scr, lane); continue; } r -= I1;
;         if (r < I2) { const int nb = r % 192, kb = r / 192; const int n0 = 64 * nb; const int j0 = n0 < DFF ? n0 : n0 - DFF;
;             const int drow = (j0 >> 7) * 256 + (n0 < DFF ? 0 : 128) + (j0 & 127);
;             cvt_item(p.in[I_WUP], 2 * DFF, (bf16_t*)(ws + WS_WUP), DM, 64 * kb, n0, drow, scr, lane); continue; } r -= I2;
;         if (r < I3) { const int nb = r % 32, kb = r / 32; cvt_item(p.in[I_WDOWN], DM, (bf16_t*)(ws + WS_WDOWN), DFF, 64 * kb, 64 * nb, 64 * nb, scr, lane); continue; } r -= I3;
.Lipf_skip_0:
	s_cmp_gt_i32 s2, 47
	s_waitcnt lgkmcnt(0)
	s_barrier
	s_cbranch_scc0 .LBB0_124
	v_add_u32_e32 v0, 0xfffffe80, v210
	s_movk_i32 s0, 0x1940
	v_cmp_gt_u32_e32 vcc, s0, v0
	s_and_saveexec_b64 s[4:5], vcc
	s_cbranch_execz .LBB0_125
	v_readlane_b32 s0, v255, 6
	v_lshlrev_b32_e32 v0, 3, v212
	v_readlane_b32 s1, v255, 7
	v_and_b32_e32 v32, 56, v0
	s_movk_i32 s1, 0x4100
	v_mov_b32_e32 v1, 0
	v_lshrrev_b32_e32 v44, 3, v184
	v_lshlrev_b32_e32 v0, 1, v32
	v_mad_u32_u24 v4, v213, s1, 0
	v_lshlrev_b32_e32 v30, 2, v184
	v_mul_u32_u24_e32 v5, 0x104, v32
	v_lshl_add_u64 v[16:17], s[84:85], 0, v[0:1]
	v_lshlrev_b32_e32 v0, 2, v44
	s_mov_b64 s[8:9], 0x5900000
	v_add_u32_e32 v43, v4, v30
	v_add3_u32 v45, v4, v5, v0
	v_lshl_add_u64 v[4:5], v[16:17], 0, s[8:9]
	s_mov_b64 s[8:9], 0x5d00000
	v_lshl_add_u64 v[6:7], v[16:17], 0, s[8:9]
	s_mov_b64 s[8:9], 0x6500000
	v_lshl_add_u64 v[8:9], v[16:17], 0, s[8:9]
	s_mov_b64 s[8:9], 0xe00000
	v_lshl_add_u64 v[10:11], v[16:17], 0, s[8:9]
	s_mov_b64 s[8:9], 0x2600000
	v_lshl_add_u64 v[12:13], v[16:17], 0, s[8:9]
	s_mov_b64 s[8:9], 0x9d00000
	s_mov_b64 s[6:7], 0x5680000
	v_lshl_add_u64 v[14:15], v[16:17], 0, s[8:9]
	s_mov_b64 s[8:9], 0x6d00000
	s_addk_i32 s0, 0xfe80
	v_lshl_add_u64 v[2:3], v[16:17], 0, s[6:7]
	v_lshl_add_u64 v[16:17], v[16:17], 0, s[8:9]
	v_readlane_b32 s8, v254, 33
	v_readlane_b32 s52, v254, 17
	s_add_u32 s6, s84, 0x5600000
	v_mov_b32_e32 v31, v1
	v_readlane_b32 s9, v254, 34
	v_readlane_b32 s10, v254, 35
	v_readlane_b32 s11, v254, 36
	v_readlane_b32 s12, v254, 37
	v_readlane_b32 s13, v254, 38
	v_readlane_b32 s14, v254, 39
	v_readlane_b32 s15, v254, 40
	v_readlane_b32 s20, v254, 45
	v_readlane_b32 s21, v254, 46
	v_readlane_b32 s22, v254, 47
	v_readlane_b32 s23, v254, 48
	v_readlane_b32 s53, v254, 18
	v_readlane_b32 s54, v254, 19
	v_readlane_b32 s55, v254, 20
	v_readlane_b32 s56, v254, 21
	v_readlane_b32 s57, v254, 22
	v_readlane_b32 s58, v254, 23
	v_readlane_b32 s59, v254, 24
	v_readlane_b32 s60, v254, 25
	v_readlane_b32 s61, v254, 26
	v_readlane_b32 s62, v254, 27
	v_readlane_b32 s63, v254, 28
	v_readlane_b32 s64, v254, 29
	v_readlane_b32 s65, v254, 30
	v_add_u32_e32 v42, 0x1680, v210
	v_or_b32_e32 v46, 8, v44
	v_or_b32_e32 v47, 16, v44
	v_or_b32_e32 v48, 24, v44
	v_or_b32_e32 v49, 32, v44
	v_or_b32_e32 v50, 40, v44
	v_or_b32_e32 v51, 48, v44
	v_or_b32_e32 v52, 56, v44
	s_addc_u32 s7, s85, 0
	v_lshl_add_u64 v[18:19], s[8:9], 0, v[30:31]
	v_lshl_add_u64 v[20:21], s[10:11], 0, v[30:31]
	v_lshl_add_u64 v[22:23], s[12:13], 0, v[30:31]
	v_lshl_add_u64 v[24:25], s[20:21], 0, v[30:31]
	v_lshl_add_u64 v[26:27], s[14:15], 0, v[30:31]
	v_lshl_add_u64 v[28:29], s[64:65], 0, v[30:31]
	v_lshl_add_u64 v[30:31], s[52:53], 0, v[30:31]
	s_movk_i32 s1, 0x25ff
	s_movk_i32 s3, 0x3dff
	s_movk_i32 s35, 0x1000
	s_movk_i32 s52, 0x2000
	s_movk_i32 s53, 0x3000
	s_movk_i32 s54, 0x4000
	s_movk_i32 s55, 0x5000
	s_movk_i32 s56, 0x6000
	s_movk_i32 s57, 0x7000
	s_mov_b32 s58, 0x8000
	s_mov_b32 s59, 0x9000
	s_mov_b32 s60, 0xa000
	s_mov_b32 s61, 0xb000
	s_mov_b32 s62, 0xc000
	s_mov_b32 s63, 0xd000
	s_mov_b32 s22, 0xe000
	s_mov_b32 s23, 0xf000
	v_lshlrev_b32_e32 v32, 1, v32
	s_mov_b32 s24, 0x54000
	s_mov_b32 s25, 0xa8000
	s_mov_b32 s82, 0xfc000
	s_mov_b32 s83, 0x150000
	v_mov_b32_e32 v53, 0x80
	v_mov_b32_e32 v54, 0xffffabc0
	v_mov_b32_e32 v55, 0xffffab40
	v_lshlrev_b32_e32 v34, 2, v184
	v_mov_b32_e32 v56, 6
	s_mov_b32 s88, 0x1a4000
	s_mov_b64 s[8:9], 0
	v_readlane_b32 s16, v254, 41
	v_readlane_b32 s17, v254, 42
	v_readlane_b32 s18, v254, 43
	v_readlane_b32 s19, v254, 44
	v_readlane_b32 s66, v254, 31
	v_readlane_b32 s67, v254, 32
	s_branch .LBB0_92
.LBB0_91:
	s_or_b64 exec, exec, s[10:11]
	v_add_u32_e32 v42, s0, v42
	s_movk_i32 s10, 0x313f
	v_cmp_lt_i32_e32 vcc, s10, v42
	s_or_b64 s[8:9], vcc, s[8:9]
	s_andn2_b64 exec, exec, s[8:9]
	s_cbranch_execz .LBB0_125
.LBB0_92:
	v_add_u32_e32 v0, 0x1800, v42
	v_cmp_lt_i32_e32 vcc, s1, v42
	s_movk_i32 s10, 0x17ff
	s_nop 0
	v_cndmask_b32_e32 v0, v42, v0, vcc
	v_add_u32_e32 v33, 0xc00, v0
	v_cmp_lt_i32_e32 vcc, s3, v0
	s_nop 1
	v_cndmask_b32_e32 v33, v0, v33, vcc
	v_cmp_lt_i32_e32 vcc, s10, v33
	s_and_saveexec_b64 s[10:11], vcc
	s_xor_b64 s[10:11], exec, s[10:11]
	s_cbranch_execz .LBB0_122
	v_cmp_lt_u32_e32 vcc, s1, v33
	s_and_saveexec_b64 s[12:13], vcc
	s_xor_b64 s[12:13], exec, s[12:13]
	s_cbranch_execz .LBB0_119
	v_cmp_lt_u32_e32 vcc, s3, v33
	s_and_saveexec_b64 s[14:15], vcc
	s_xor_b64 s[14:15], exec, s[14:15]
	s_cbranch_execz .LBB0_116
	s_movk_i32 s16, 0x49ff
	v_cmp_lt_u32_e32 vcc, s16, v33
	s_and_saveexec_b64 s[16:17], vcc
	s_xor_b64 s[16:17], exec, s[16:17]
	s_cbranch_execz .LBB0_113
	s_movk_i32 s18, 0x4dff
	v_cmp_lt_u32_e32 vcc, s18, v33
	s_and_saveexec_b64 s[18:19], vcc
	s_xor_b64 s[18:19], exec, s[18:19]
	s_cbranch_execz .LBB0_110
	s_movk_i32 s20, 0x51ff
	v_cmp_lt_u32_e32 vcc, s20, v33
	s_and_saveexec_b64 s[20:21], vcc
	s_xor_b64 s[20:21], exec, s[20:21]
	s_cbranch_execz .LBB0_107
	s_movk_i32 s33, 0x53ff
	v_cmp_lt_u32_e32 vcc, s33, v33
	s_and_saveexec_b64 s[40:41], vcc
	s_xor_b64 s[40:41], exec, s[40:41]
	s_cbranch_execz .LBB0_104
	s_movk_i32 s33, 0x543f
	v_cmp_lt_u32_e32 vcc, s33, v33
	s_and_saveexec_b64 s[42:43], vcc
	s_xor_b64 s[42:43], exec, s[42:43]
	s_cbranch_execz .LBB0_101
; #define LAS __attribute__((address_space(3)))
; __device__ __forceinline__ void cvt_item(const float* __restrict__ W, int N, bf16_t* WT, int K, int k0, int n0, int drow0, LAS float* scr, int lane) {
;     float v[64];
; #pragma unroll
;     for (int kk = 0; kk < 64; ++kk) v[kk] = __builtin_nontemporal_load(W + (size_t)(k0 + kk) * N + n0 + lane);
; template <int PART> __device__ __forceinline__ void phase0(const Params& p, LAS unsigned char* lds) {
;     ...
;         { const bool isig = r >= I8; if (isig) r -= I8;
;           const int blk = r >> 4, q = r & 15, kb = q >> 2, nb = q & 3, n0 = 64 * nb;
;           const int drow = (blk * 2 + (n0 >> 7)) * 256 + (isig ? 128 : 0) + (n0 & 127);
;           cvt_item(p.in[isig ? I_WIG : I_WRG] + (size_t)blk * 65536, 256, (bf16_t*)(ws + WS_WGATE), 256, 64 * kb, n0, drow, scr, lane); }
	s_movk_i32 s33, 0x54bf
	v_cmp_lt_u32_e32 vcc, s33, v33
	s_movk_i32 s33, 0x100
	v_readlane_b32 s64, v254, 49
	v_cndmask_b32_e32 v0, v54, v55, vcc
	v_add_u32_e32 v40, v0, v33
	v_lshrrev_b32_e32 v0, 4, v40
	v_lshlrev_b32_e32 v33, 6, v40
	v_lshlrev_b32_e32 v36, 9, v0
	v_lshlrev_b32_e32 v37, 7, v40
	v_cndmask_b32_e32 v35, 0, v53, vcc
	v_and_or_b32 v36, v37, s33, v36
	v_and_b32_e32 v33, 64, v33
	v_readlane_b32 s71, v254, 56
	v_readlane_b32 s75, v254, 60
	v_or3_b32 v33, v36, v35, v33
	v_readlane_b32 s70, v254, 55
	v_readlane_b32 s74, v254, 59
	v_mov_b32_e32 v35, s71
	v_mov_b32_e32 v36, s75
	v_cndmask_b32_e32 v37, v35, v36, vcc
	v_mov_b32_e32 v35, s70
	v_mov_b32_e32 v36, s74
	v_lshlrev_b64 v[38:39], 18, v[0:1]
	v_lshlrev_b32_e32 v0, 4, v40
	v_cndmask_b32_e32 v36, v35, v36, vcc
	v_and_b32_e32 v57, 0xc0, v0
	v_lshlrev_b32_e32 v0, 8, v40
	v_lshl_add_u64 v[36:37], v[36:37], 0, v[38:39]
	v_and_b32_e32 v0, 0x300, v0
	v_lshl_add_u64 v[36:37], v[36:37], 0, v[0:1]
	v_mov_b32_e32 v35, v1
	v_lshl_add_u64 v[36:37], v[36:37], 0, v[34:35]
	v_lshlrev_b32_e32 v0, 10, v57
	v_lshl_add_u64 v[36:37], v[36:37], 0, v[0:1]
	v_add_co_u32_e32 v38, vcc, s35, v36
	global_load_dword v0, v[36:37], off nt
	global_load_dword v35, v[36:37], off offset:1024 nt
	global_load_dword v58, v[36:37], off offset:2048 nt
	global_load_dword v59, v[36:37], off offset:3072 nt
	v_addc_co_u32_e32 v39, vcc, 0, v37, vcc
	v_add_co_u32_e32 v40, vcc, s52, v36
	v_readlane_b32 s65, v254, 50
	s_nop 0
	v_addc_co_u32_e32 v41, vcc, 0, v37, vcc
	global_load_dword v60, v[40:41], off offset:-4096 nt
	global_load_dword v61, v[38:39], off offset:1024 nt
	global_load_dword v62, v[38:39], off offset:2048 nt
	global_load_dword v63, v[38:39], off offset:3072 nt
	global_load_dword v64, v[40:41], off nt
	global_load_dword v65, v[40:41], off offset:1024 nt
	global_load_dword v66, v[40:41], off offset:2048 nt
	global_load_dword v67, v[40:41], off offset:3072 nt
	v_add_co_u32_e32 v38, vcc, s53, v36
	v_readlane_b32 s66, v254, 51
	s_nop 0
	v_addc_co_u32_e32 v39, vcc, 0, v37, vcc
	v_add_co_u32_e32 v40, vcc, s54, v36
	v_readlane_b32 s67, v254, 52
	s_nop 0
	v_addc_co_u32_e32 v41, vcc, 0, v37, vcc
	global_load_dword v68, v[40:41], off offset:-4096 nt
	global_load_dword v69, v[38:39], off offset:1024 nt
	global_load_dword v70, v[38:39], off offset:2048 nt
	global_load_dword v71, v[38:39], off offset:3072 nt
	global_load_dword v72, v[40:41], off nt
	global_load_dword v73, v[40:41], off offset:1024 nt
	global_load_dword v74, v[40:41], off offset:2048 nt
	global_load_dword v75, v[40:41], off offset:3072 nt
	v_add_co_u32_e32 v38, vcc, s55, v36
	v_readlane_b32 s68, v254, 53
	s_nop 0
	v_addc_co_u32_e32 v39, vcc, 0, v37, vcc
	v_add_co_u32_e32 v40, vcc, s56, v36
	v_readlane_b32 s69, v254, 54
	s_nop 0
	v_addc_co_u32_e32 v41, vcc, 0, v37, vcc
	global_load_dword v76, v[40:41], off offset:-4096 nt
	global_load_dword v77, v[38:39], off offset:1024 nt
	global_load_dword v78, v[38:39], off offset:2048 nt
	global_load_dword v79, v[38:39], off offset:3072 nt
	global_load_dword v80, v[40:41], off nt
	global_load_dword v81, v[40:41], off offset:1024 nt
	global_load_dword v82, v[40:41], off offset:2048 nt
	global_load_dword v83, v[40:41], off offset:3072 nt
	v_add_co_u32_e32 v38, vcc, s57, v36
	v_readlane_b32 s72, v254, 57
	s_nop 0
	v_addc_co_u32_e32 v39, vcc, 0, v37, vcc
	v_add_co_u32_e32 v40, vcc, s58, v36
	v_readlane_b32 s73, v254, 58
	s_nop 0
	v_addc_co_u32_e32 v41, vcc, 0, v37, vcc
	global_load_dword v84, v[40:41], off offset:-4096 nt
	global_load_dword v85, v[38:39], off offset:1024 nt
	global_load_dword v86, v[38:39], off offset:2048 nt
	global_load_dword v87, v[38:39], off offset:3072 nt
	global_load_dword v88, v[40:41], off nt
	global_load_dword v89, v[40:41], off offset:1024 nt
	global_load_dword v90, v[40:41], off offset:2048 nt
	global_load_dword v91, v[40:41], off offset:3072 nt
	v_add_co_u32_e32 v38, vcc, s59, v36
	v_readlane_b32 s76, v254, 61
	s_nop 0
	v_addc_co_u32_e32 v39, vcc, 0, v37, vcc
	v_add_co_u32_e32 v40, vcc, s60, v36
	v_readlane_b32 s77, v254, 62
	s_nop 0
	v_addc_co_u32_e32 v41, vcc, 0, v37, vcc
	global_load_dword v92, v[40:41], off offset:-4096 nt
	global_load_dword v93, v[38:39], off offset:1024 nt
	global_load_dword v94, v[38:39], off offset:2048 nt
	global_load_dword v95, v[38:39], off offset:3072 nt
	global_load_dword v96, v[40:41], off nt
	global_load_dword v97, v[40:41], off offset:1024 nt
	global_load_dword v98, v[40:41], off offset:2048 nt
	global_load_dword v99, v[40:41], off offset:3072 nt
	v_add_co_u32_e32 v38, vcc, s61, v36
	v_readlane_b32 s78, v254, 63
	s_nop 0
	v_addc_co_u32_e32 v39, vcc, 0, v37, vcc
	v_add_co_u32_e32 v40, vcc, s62, v36
	v_readlane_b32 s79, v255, 0
	s_nop 0
	v_addc_co_u32_e32 v41, vcc, 0, v37, vcc
	global_load_dword v100, v[40:41], off offset:-4096 nt
	global_load_dword v101, v[38:39], off offset:1024 nt
	global_load_dword v102, v[38:39], off offset:2048 nt
	global_load_dword v103, v[38:39], off offset:3072 nt
	global_load_dword v104, v[40:41], off nt
	global_load_dword v105, v[40:41], off offset:1024 nt
	global_load_dword v106, v[40:41], off offset:2048 nt
	global_load_dword v107, v[40:41], off offset:3072 nt
	v_add_co_u32_e32 v38, vcc, s63, v36
	s_nop 1
	v_addc_co_u32_e32 v39, vcc, 0, v37, vcc
	v_add_co_u32_e32 v40, vcc, s22, v36
	s_nop 1
	v_addc_co_u32_e32 v41, vcc, 0, v37, vcc
	v_add_co_u32_e32 v36, vcc, s23, v36
	global_load_dword v108, v[40:41], off offset:-4096 nt
	global_load_dword v109, v[38:39], off offset:1024 nt
	global_load_dword v110, v[38:39], off offset:2048 nt
	s_nop 0
	global_load_dword v38, v[38:39], off offset:3072 nt
	s_nop 0
	global_load_dword v39, v[40:41], off nt
	global_load_dword v111, v[40:41], off offset:1024 nt
	global_load_dword v112, v[40:41], off offset:2048 nt
	s_nop 0
	global_load_dword v40, v[40:41], off offset:3072 nt
	v_addc_co_u32_e32 v37, vcc, 0, v37, vcc
	global_load_dword v41, v[36:37], off nt
	global_load_dword v113, v[36:37], off offset:1024 nt
	global_load_dword v114, v[36:37], off offset:2048 nt
	s_nop 0
	global_load_dword v36, v[36:37], off offset:3072 nt
	s_waitcnt vmcnt(62)
; #define LAS __attribute__((address_space(3)))
; __device__ __forceinline__ unsigned pk2(float lo, float hi) { unsigned r; asm("v_cvt_pk_bf16_f32 %0, %1, %2" : "=v"(r) : "v"(lo), "v"(hi)); return r; }
; __device__ __forceinline__ void cvt_item(const float* __restrict__ W, int N, bf16_t* WT, int K, int k0, int n0, int drow0, LAS float* scr, int lane) {
;     ...
; #pragma unroll
;     for (int kk = 0; kk < 64; ++kk) scr[kk * 65 + lane] = v[kk];
;     asm volatile("s_waitcnt lgkmcnt(0)" ::: "memory");
;     const int c = lane & 7;
; #pragma unroll
;     for (int j = 0; j < 8; ++j) { const int n = (lane >> 3) + 8 * j; const LAS float* s = scr + (8 * c) * 65 + n;
;         u32x4 o; o.x = pk2(s[0 * 65], s[1 * 65]); o.y = pk2(s[2 * 65], s[3 * 65]); o.z = pk2(s[4 * 65], s[5 * 65]); o.w = pk2(s[6 * 65], s[7 * 65]);
;         *(u32x4*)(WT + (size_t)(drow0 + n) * K + k0 + 8 * c) = o; }
	ds_write2_b32 v43, v0, v35 offset1:65
	s_waitcnt vmcnt(60)
	ds_write2_b32 v43, v58, v59 offset0:130 offset1:195
	v_add_u32_e32 v0, 0x400, v43
	s_waitcnt vmcnt(58)
	ds_write2_b32 v0, v60, v61 offset0:4 offset1:69
	s_waitcnt vmcnt(56)
	ds_write2_b32 v0, v62, v63 offset0:134 offset1:199
	v_add_u32_e32 v0, 0x800, v43
	s_waitcnt vmcnt(54)
	ds_write2_b32 v0, v64, v65 offset0:8 offset1:73
	s_waitcnt vmcnt(52)
	ds_write2_b32 v0, v66, v67 offset0:138 offset1:203
	v_add_u32_e32 v0, 0xc00, v43
	s_waitcnt vmcnt(50)
	ds_write2_b32 v0, v68, v69 offset0:12 offset1:77
	s_waitcnt vmcnt(48)
	ds_write2_b32 v0, v70, v71 offset0:142 offset1:207
	v_add_u32_e32 v0, 0x1000, v43
	s_waitcnt vmcnt(46)
	ds_write2_b32 v0, v72, v73 offset0:16 offset1:81
	s_waitcnt vmcnt(44)
	ds_write2_b32 v0, v74, v75 offset0:146 offset1:211
	v_add_u32_e32 v0, 0x1400, v43
	s_waitcnt vmcnt(42)
	ds_write2_b32 v0, v76, v77 offset0:20 offset1:85
	s_waitcnt vmcnt(40)
	ds_write2_b32 v0, v78, v79 offset0:150 offset1:215
	v_add_u32_e32 v0, 0x1800, v43
	s_waitcnt vmcnt(38)
	ds_write2_b32 v0, v80, v81 offset0:24 offset1:89
	s_waitcnt vmcnt(36)
	ds_write2_b32 v0, v82, v83 offset0:154 offset1:219
	v_add_u32_e32 v0, 0x1c00, v43
	s_waitcnt vmcnt(34)
	ds_write2_b32 v0, v84, v85 offset0:28 offset1:93
	s_waitcnt vmcnt(32)
	ds_write2_b32 v0, v86, v87 offset0:158 offset1:223
	v_add_u32_e32 v0, 0x2000, v43
	s_waitcnt vmcnt(30)
	ds_write2_b32 v0, v88, v89 offset0:32 offset1:97
	s_waitcnt vmcnt(28)
	ds_write2_b32 v0, v90, v91 offset0:162 offset1:227
	v_add_u32_e32 v0, 0x2400, v43
	s_waitcnt vmcnt(26)
	ds_write2_b32 v0, v92, v93 offset0:36 offset1:101
	s_waitcnt vmcnt(24)
	ds_write2_b32 v0, v94, v95 offset0:166 offset1:231
	v_add_u32_e32 v0, 0x2800, v43
	s_waitcnt vmcnt(22)
	ds_write2_b32 v0, v96, v97 offset0:40 offset1:105
	s_waitcnt vmcnt(20)
	ds_write2_b32 v0, v98, v99 offset0:170 offset1:235
	v_add_u32_e32 v0, 0x2c00, v43
	s_waitcnt vmcnt(18)
	ds_write2_b32 v0, v100, v101 offset0:44 offset1:109
	s_waitcnt vmcnt(16)
	ds_write2_b32 v0, v102, v103 offset0:174 offset1:239
	v_add_u32_e32 v0, 0x3000, v43
	s_waitcnt vmcnt(14)
	ds_write2_b32 v0, v104, v105 offset0:48 offset1:113
	s_waitcnt vmcnt(12)
	ds_write2_b32 v0, v106, v107 offset0:178 offset1:243
	v_add_u32_e32 v0, 0x3400, v43
	s_waitcnt vmcnt(10)
	ds_write2_b32 v0, v108, v109 offset0:52 offset1:117
	s_waitcnt vmcnt(8)
	ds_write2_b32 v0, v110, v38 offset0:182 offset1:247
	v_add_u32_e32 v0, 0x3800, v43
	s_waitcnt vmcnt(6)
	ds_write2_b32 v0, v39, v111 offset0:56 offset1:121
	s_waitcnt vmcnt(4)
	ds_write2_b32 v0, v112, v40 offset0:186 offset1:251
	v_add_u32_e32 v0, 0x3c00, v43
	s_waitcnt vmcnt(2)
	ds_write2_b32 v0, v41, v113 offset0:60 offset1:125
	s_waitcnt vmcnt(0)
	ds_write2_b32 v0, v114, v36 offset0:190 offset1:255
	s_waitcnt lgkmcnt(0)
	v_lshlrev_b32_e32 v0, 1, v57
	v_lshl_add_u64 v[36:37], v[2:3], 0, v[0:1]
	ds_read2_b32 v[58:59], v45 offset0:65 offset1:73
	ds_read2_b32 v[60:61], v45 offset1:8
	v_add_u32_e32 v0, 0x400, v45
	ds_read2_b32 v[62:63], v45 offset0:130 offset1:138
	ds_read2_b32 v[64:65], v45 offset0:195 offset1:203
	ds_read2_b32 v[66:67], v0 offset0:4 offset1:12
	ds_read2_b32 v[68:69], v0 offset0:69 offset1:77
	ds_read2_b32 v[70:71], v0 offset0:134 offset1:142
	ds_read2_b32 v[72:73], v0 offset0:199 offset1:207
	v_or_b32_e32 v74, v33, v44
	v_ashrrev_i32_e32 v75, 31, v74
	v_lshlrev_b64 v[74:75], 9, v[74:75]
	s_waitcnt lgkmcnt(6)
	v_cvt_pk_bf16_f32 v38, v60, v58
	v_lshl_add_u64 v[74:75], v[36:37], 0, v[74:75]
	v_or_b32_e32 v58, v33, v46
	s_waitcnt lgkmcnt(4)
	v_cvt_pk_bf16_f32 v39, v62, v64
	s_waitcnt lgkmcnt(2)
	v_cvt_pk_bf16_f32 v40, v66, v68
	s_waitcnt lgkmcnt(0)
; #define LAS __attribute__((address_space(3)))
; __device__ __forceinline__ unsigned pk2(float lo, float hi) { unsigned r; asm("v_cvt_pk_bf16_f32 %0, %1, %2" : "=v"(r) : "v"(lo), "v"(hi)); return r; }
; __device__ __forceinline__ void cvt_item(const float* __restrict__ W, int N, bf16_t* WT, int K, int k0, int n0, int drow0, LAS float* scr, int lane) {
;     ...
; #pragma unroll
;     for (int j = 0; j < 8; ++j) { const int n = (lane >> 3) + 8 * j; const LAS float* s = scr + (8 * c) * 65 + n;
;         u32x4 o; o.x = pk2(s[0 * 65], s[1 * 65]); o.y = pk2(s[2 * 65], s[3 * 65]); o.z = pk2(s[4 * 65], s[5 * 65]); o.w = pk2(s[6 * 65], s[7 * 65]);
;         *(u32x4*)(WT + (size_t)(drow0 + n) * K + k0 + 8 * c) = o; }
;     asm volatile("s_waitcnt lgkmcnt(0)" ::: "memory");
	v_cvt_pk_bf16_f32 v41, v70, v72
	global_store_dwordx4 v[74:75], v[38:41], off
	v_or_b32_e32 v74, v33, v47
	v_ashrrev_i32_e32 v75, 31, v74
	v_cvt_pk_bf16_f32 v38, v61, v59
	v_ashrrev_i32_e32 v59, 31, v58
	v_lshlrev_b64 v[58:59], 9, v[58:59]
	v_lshl_add_u64 v[58:59], v[36:37], 0, v[58:59]
	v_cvt_pk_bf16_f32 v39, v63, v65
	v_cvt_pk_bf16_f32 v40, v67, v69
	v_cvt_pk_bf16_f32 v41, v71, v73
	global_store_dwordx4 v[58:59], v[38:41], off
	ds_read2_b32 v[58:59], v45 offset0:16 offset1:24
	ds_read2_b32 v[60:61], v45 offset0:81 offset1:89
	ds_read2_b32 v[62:63], v45 offset0:146 offset1:154
	ds_read2_b32 v[64:65], v45 offset0:211 offset1:219
	ds_read2_b32 v[66:67], v0 offset0:20 offset1:28
	ds_read2_b32 v[68:69], v0 offset0:85 offset1:93
	ds_read2_b32 v[70:71], v0 offset0:150 offset1:158
	ds_read2_b32 v[72:73], v0 offset0:215 offset1:223
	v_lshlrev_b64 v[74:75], 9, v[74:75]
	s_waitcnt lgkmcnt(6)
	v_cvt_pk_bf16_f32 v38, v58, v60
	v_lshl_add_u64 v[74:75], v[36:37], 0, v[74:75]
	v_or_b32_e32 v58, v33, v48
	s_waitcnt lgkmcnt(4)
	v_cvt_pk_bf16_f32 v39, v62, v64
	s_waitcnt lgkmcnt(2)
	v_cvt_pk_bf16_f32 v40, v66, v68
	s_waitcnt lgkmcnt(0)
	v_cvt_pk_bf16_f32 v41, v70, v72
	global_store_dwordx4 v[74:75], v[38:41], off
	v_or_b32_e32 v74, v33, v49
	v_ashrrev_i32_e32 v75, 31, v74
	v_cvt_pk_bf16_f32 v38, v59, v61
	v_ashrrev_i32_e32 v59, 31, v58
	v_lshlrev_b64 v[58:59], 9, v[58:59]
	v_lshl_add_u64 v[58:59], v[36:37], 0, v[58:59]
	v_cvt_pk_bf16_f32 v39, v63, v65
	v_cvt_pk_bf16_f32 v40, v67, v69
	v_cvt_pk_bf16_f32 v41, v71, v73
	global_store_dwordx4 v[58:59], v[38:41], off
	ds_read2_b32 v[58:59], v45 offset0:32 offset1:40
	ds_read2_b32 v[60:61], v45 offset0:97 offset1:105
	ds_read2_b32 v[62:63], v45 offset0:162 offset1:170
	ds_read2_b32 v[64:65], v45 offset0:227 offset1:235
	ds_read2_b32 v[66:67], v0 offset0:36 offset1:44
	ds_read2_b32 v[68:69], v0 offset0:101 offset1:109
	ds_read2_b32 v[70:71], v0 offset0:166 offset1:174
	ds_read2_b32 v[72:73], v0 offset0:231 offset1:239
	v_lshlrev_b64 v[74:75], 9, v[74:75]
	s_waitcnt lgkmcnt(6)
	v_cvt_pk_bf16_f32 v38, v58, v60
	v_lshl_add_u64 v[74:75], v[36:37], 0, v[74:75]
	v_or_b32_e32 v58, v33, v50
	s_waitcnt lgkmcnt(4)
	v_cvt_pk_bf16_f32 v39, v62, v64
	s_waitcnt lgkmcnt(2)
	v_cvt_pk_bf16_f32 v40, v66, v68
	s_waitcnt lgkmcnt(0)
	v_cvt_pk_bf16_f32 v41, v70, v72
	global_store_dwordx4 v[74:75], v[38:41], off
	v_or_b32_e32 v74, v33, v51
	v_ashrrev_i32_e32 v75, 31, v74
	v_cvt_pk_bf16_f32 v38, v59, v61
	v_ashrrev_i32_e32 v59, 31, v58
	v_lshlrev_b64 v[58:59], 9, v[58:59]
	v_lshl_add_u64 v[58:59], v[36:37], 0, v[58:59]
	v_cvt_pk_bf16_f32 v39, v63, v65
	v_cvt_pk_bf16_f32 v40, v67, v69
	v_cvt_pk_bf16_f32 v41, v71, v73
	global_store_dwordx4 v[58:59], v[38:41], off
	ds_read2_b32 v[58:59], v45 offset0:48 offset1:56
	ds_read2_b32 v[60:61], v45 offset0:113 offset1:121
	ds_read2_b32 v[62:63], v45 offset0:178 offset1:186
	ds_read2_b32 v[64:65], v45 offset0:243 offset1:251
	ds_read2_b32 v[66:67], v0 offset0:52 offset1:60
	ds_read2_b32 v[68:69], v0 offset0:117 offset1:125
	ds_read2_b32 v[70:71], v0 offset0:182 offset1:190
	ds_read2_b32 v[72:73], v0 offset0:247 offset1:255
	v_lshlrev_b64 v[74:75], 9, v[74:75]
	s_waitcnt lgkmcnt(6)
	v_cvt_pk_bf16_f32 v38, v58, v60
	v_lshl_add_u64 v[74:75], v[36:37], 0, v[74:75]
	v_or_b32_e32 v58, v33, v52
	s_waitcnt lgkmcnt(4)
	v_cvt_pk_bf16_f32 v39, v62, v64
	s_waitcnt lgkmcnt(2)
	v_cvt_pk_bf16_f32 v40, v66, v68
	s_waitcnt lgkmcnt(0)
	v_cvt_pk_bf16_f32 v41, v70, v72
	global_store_dwordx4 v[74:75], v[38:41], off
	s_nop 1
	v_cvt_pk_bf16_f32 v38, v59, v61
	v_ashrrev_i32_e32 v59, 31, v58
	v_lshlrev_b64 v[58:59], 9, v[58:59]
	v_lshl_add_u64 v[36:37], v[36:37], 0, v[58:59]
	v_cvt_pk_bf16_f32 v39, v63, v65
	v_cvt_pk_bf16_f32 v40, v67, v69
	v_cvt_pk_bf16_f32 v41, v71, v73
	global_store_dwordx4 v[36:37], v[38:41], off
	s_waitcnt lgkmcnt(0)

; #define LAS __attribute__((address_space(3)))
; template <int PART> __device__ __forceinline__ void phase0(const Params& p, LAS unsigned char* lds) {
;     constexpr int SKIP = PART == 0 ? 0 : PART == 1 ? 48 : 192;
;     const int tid = threadIdx.x, lane = tid & 63, wave = tid >> 6;
;     const int gw = ((int)blockIdx.x - SKIP) * NWAVES + wave, NGW = ((int)gridDim.x - SKIP) * NWAVES;
;     if (gw < 0) return;
;     const int gt = blockIdx.x * NTHREADS + tid, NGT = gridDim.x * NTHREADS;
;     unsigned char* ws = p.ws;
;     LAS float* scr = (LAS float*)(lds + wave * 16640);
;     constexpr int I0 = 32 * 192, I1 = 32 * 112, I2 = 32 * 192, I3 = 96 * 32, I4 = 32 * 32, I5 = 32 * 32, I6 = 16 * 32, I7 = 64, I8 = 128, I9 = 128;
;     constexpr int NIT = I0 + I1 + I2 + I3 + I4 + I5 + I6 + I7 + I8 + I9;
;     constexpr int U0 = I0 + I1, U1 = U0 + I2 / 2, D0 = I0 + I1 + I2, D1 = D0 + I3;
;     constexpr int CUT = (U1 - U0) + I3;
;     constexpr int LO = PART == 0 ? 0 : PART == 1 ? I0 : PART == 2 ? U0 : D0, HI = PART == 0 ? I0 : PART == 1 ? NIT - CUT : PART == 2 ? U1 : D1;
;     for (int it0 = LO + gw; it0 < HI; it0 += NGW) {
;         int it = it0;
;         if (PART == 1) { if (it >= U0) it += U1 - U0; if (it >= D0) it += I3; }
.LBB0_975:
	v_readlane_b32 s0, v255, 6
	v_add_u32_e32 v0, 0xfffffa00, v210
	s_add_i32 s34, s0, 0xfffffa00
	s_movk_i32 s0, 0xc00
	v_cmp_gt_u32_e64 s[50:51], s0, v0
	v_add_u32_e32 v0, 0xfffffe00, v210
	s_movk_i32 s0, 0x1800
	v_cmp_gt_u32_e32 vcc, s0, v0
	v_readlane_b32 s99, v255, 6
	s_add_i32 s99, s99, 0xfffffe00
	v_lshrrev_b32_e32 v221, 3, v184
	v_readlane_b32 s1, v255, 7
	s_and_saveexec_b64 s[8:9], vcc
	s_cbranch_execz .LBB0_986
	v_and_b32_e32 v0, 56, v217
	s_movk_i32 s0, 0x4100
	v_mul_u32_u24_e32 v5, 0x104, v0
	v_lshlrev_b32_e32 v0, 1, v0
	v_mov_b32_e32 v1, 0
	v_readlane_b32 s12, v254, 33
	v_mad_u32_u24 v4, v213, s0, 0
	v_lshl_add_u64 v[2:3], s[84:85], 0, v[0:1]
	s_mov_b64 s[0:1], 0x2600000
	v_mov_b32_e32 v219, v1
	v_readlane_b32 s13, v254, 34
	v_readlane_b32 s14, v254, 35
	v_readlane_b32 s15, v254, 36
	v_readlane_b32 s16, v254, 37
	v_readlane_b32 s17, v254, 38
	v_readlane_b32 s18, v254, 39
	v_readlane_b32 s19, v254, 40
	v_readlane_b32 s20, v254, 41
	v_readlane_b32 s21, v254, 42
	v_readlane_b32 s22, v254, 43
	v_readlane_b32 s23, v254, 44
	v_readlane_b32 s24, v254, 45
	v_readlane_b32 s25, v254, 46
	v_readlane_b32 s26, v254, 47
	v_readlane_b32 s27, v254, 48
	v_lshl_add_u64 v[2:3], v[2:3], 0, s[0:1]
	v_readlane_b32 s0, v255, 12
	v_lshl_add_u64 v[8:9], s[18:19], 0, v[218:219]
	v_readlane_b32 s12, v254, 17
	v_lshlrev_b32_e32 v6, 2, v221
	v_readlane_b32 s1, v255, 13
	v_readlane_b32 s13, v254, 18
	v_readlane_b32 s24, v254, 29
	v_readlane_b32 s25, v254, 30
	v_add_u32_e32 v15, 0x2400, v210
	v_add_u32_e32 v22, v4, v218
	v_add3_u32 v23, v4, v5, v6
	v_lshl_add_u64 v[4:5], s[0:1], 0, v[0:1]
	v_readlane_b32 s16, v254, 21
	v_readlane_b32 s17, v254, 22
	v_readlane_b32 s18, v254, 23
	v_readlane_b32 s19, v254, 24
	v_readlane_b32 s20, v254, 25
	v_readlane_b32 s21, v254, 26
	s_mov_b64 s[0:1], s[12:13]
	s_mov_b64 s[12:13], s[24:25]
	v_or_b32_e32 v24, 8, v221
	v_or_b32_e32 v25, 16, v221
	v_or_b32_e32 v26, 24, v221
	v_or_b32_e32 v27, 32, v221
	v_or_b32_e32 v28, 40, v221
	v_or_b32_e32 v29, 48, v221
	v_or_b32_e32 v30, 56, v221
	v_lshl_add_u64 v[6:7], s[44:45], 0, v[0:1]
	v_lshl_add_u64 v[10:11], s[12:13], 0, v[218:219]
	v_lshl_add_u64 v[12:13], s[0:1], 0, v[218:219]
	v_lshlrev_b32_e32 v14, 6, v15
	s_lshl_b32 s0, s99, 6
	s_mov_b32 s1, 0xc000
	s_mov_b32 s4, 0x54000
	s_mov_b32 s5, 0xa8000
	s_mov_b32 s16, 0xfc000
	s_mov_b32 s17, 0x150000
	s_mov_b32 s18, 0x1a4000
	s_mov_b32 s19, 0x1ec000
	s_mov_b32 s20, 0x1f8000
	s_mov_b32 s21, 0x204000
	s_mov_b32 s35, 0x210000
	s_mov_b32 s46, 0x21c000
	s_mov_b32 s47, 0x228000
	s_mov_b32 s48, 0x234000
	s_mov_b32 s49, 0x240000
	s_mov_b32 s52, 0x24c000
	s_mov_b32 s53, 0x258000
	v_mov_b32_e32 v31, 0x80
	v_add_u32_e32 v32, 0x400, v22
	v_add_u32_e32 v33, 0x800, v22
	v_add_u32_e32 v34, 0xc00, v22
	v_add_u32_e32 v35, 0x1000, v22
	v_add_u32_e32 v36, 0x1400, v22
	v_add_u32_e32 v37, 0x1800, v22
	v_add_u32_e32 v38, 0x1c00, v22
	v_add_u32_e32 v39, 0x2000, v22
	v_add_u32_e32 v40, 0x2400, v22
	v_add_u32_e32 v41, 0x2800, v22
	v_add_u32_e32 v42, 0x2c00, v22
	v_add_u32_e32 v43, 0x3000, v22
	v_add_u32_e32 v44, 0x3400, v22
	v_add_u32_e32 v45, 0x3800, v22
	v_add_u32_e32 v46, 0x3c00, v22
	v_add_u32_e32 v47, 0x400, v23
	v_mov_b32_e32 v48, 6
	s_mov_b32 s54, 0x264000
	s_mov_b32 s55, 0x270000
	s_mov_b32 s56, 0x27c000
	s_mov_b32 s57, 0x288000
	s_mov_b32 s58, 0x294000
	s_mov_b32 s59, 0x2a0000
	s_mov_b32 s60, 0x2ac000
	s_mov_b32 s61, 0x2b8000
	s_mov_b32 s62, 0x2c4000
	s_mov_b32 s63, 0x2d0000
	s_mov_b32 s64, 0x2dc000
	s_mov_b32 s65, 0x2e8000
	s_mov_b32 s66, 0x2f4000
	s_movk_i32 s67, 0x70
	s_movk_i32 s68, 0x7000
	s_mov_b32 s69, 0x2aaaaaab
	s_movk_i32 s70, 0xd000
	s_movk_i32 s71, 0x3dff
	s_mov_b64 s[10:11], 0
	v_readlane_b32 s14, v254, 19
	v_readlane_b32 s15, v254, 20
	v_readlane_b32 s22, v254, 27
	v_readlane_b32 s23, v254, 28
	v_readlane_b32 s26, v254, 31
	v_readlane_b32 s27, v254, 32
	s_branch .LBB0_978
.LBB0_977:
	s_or_b64 exec, exec, s[12:13]
	v_add_u32_e32 v15, s99, v15
	v_cmp_lt_i32_e32 vcc, s71, v15
	s_or_b64 s[10:11], vcc, s[10:11]
	v_add_u32_e32 v14, s0, v14
	s_andn2_b64 exec, exec, s[10:11]
	s_cbranch_execz .LBB0_986
